# v40 + SWA task: first two QK tiles keep 6 K-fragment LDS reads in flight (task-dead registers as extra buffers), counted waits
# speedup vs baseline: 1.0047x; 1.0047x over previous
.LBB0_484:
	s_lshr_b32 s16, s42, 1
	s_lshl_b32 s17, s16, 6
	s_mulk_i32 s16, 0x4100
	v_lshl_add_u64 v[0:1], s[4:5], 1, v[156:157]
	s_add_i32 s16, s16, 0
	global_load_dwordx4 v[124:127], v[0:1], off
	global_load_dwordx4 v[120:123], v[0:1], off offset:1024
	global_load_dwordx4 v[116:119], v[0:1], off offset:2048
	global_load_dwordx4 v[112:115], v[0:1], off offset:3072
	v_add_u32_e32 v0, s16, v149
	v_add_u32_e32 v239, v0, v166
	ds_read_b128 v[0:3], v239
	ds_read_b128 v[16:19], v239 offset:512
	ds_read_b128 v[32:35], v239 offset:2080
	ds_read_b128 v[36:39], v239 offset:2592
	ds_read_b128 v[44:47], v239 offset:4160
	ds_read_b128 v[52:55], v239 offset:4672
	ds_read_b128 v[56:59], v239 offset:6240
	ds_read_b128 v[60:63], v239 offset:6752
	s_waitcnt lgkmcnt(7)
	v_mfma_f32_32x32x16_bf16 v[0:15], v[0:3], v[48:51], 0
	v_subrev_u32_e32 v40, s17, v197
	v_add_u32_e32 v200, v140, v40
	v_add_u32_e32 v41, s41, v140
	v_cvt_f32_u32_e32 v240, v41
	s_movk_i32 s4, 0x7f
	s_waitcnt lgkmcnt(6)
	v_mfma_f32_32x32x16_bf16 v[16:31], v[16:19], v[48:51], 0
	s_waitcnt lgkmcnt(5)
	v_mfma_f32_32x32x16_bf16 v[0:15], v[32:35], v[136:139], v[0:15]
	ds_read_b128 v[32:35], v239 offset:16640
	s_waitcnt lgkmcnt(5)
	v_mfma_f32_32x32x16_bf16 v[16:31], v[36:39], v[136:139], v[16:31]
	ds_read_b128 v[36:39], v239 offset:17152
	s_waitcnt lgkmcnt(5)
	v_mfma_f32_32x32x16_bf16 v[0:15], v[44:47], v[132:135], v[0:15]
	ds_read_b128 v[44:47], v239 offset:18720
	s_waitcnt lgkmcnt(5)
	v_mfma_f32_32x32x16_bf16 v[16:31], v[52:55], v[132:135], v[16:31]
	ds_read_b128 v[52:55], v239 offset:19232
	s_waitcnt lgkmcnt(5)
	v_mfma_f32_32x32x16_bf16 v[0:15], v[56:59], v[128:131], v[0:15]
	ds_read_b128 v[56:59], v239 offset:20800
	s_waitcnt lgkmcnt(5)
	v_mfma_f32_32x32x16_bf16 v[16:31], v[60:63], v[128:131], v[16:31]
	ds_read_b128 v[60:63], v239 offset:21312
	s_waitcnt lgkmcnt(5)
	v_mfma_f32_32x32x16_bf16 v[64:79], v[32:35], v[48:51], 0
	ds_read_b128 v[32:35], v239 offset:22880
	s_waitcnt lgkmcnt(5)
	v_mfma_f32_32x32x16_bf16 v[80:95], v[36:39], v[48:51], 0
	ds_read_b128 v[36:39], v239 offset:23392
	s_waitcnt lgkmcnt(5)
	v_mfma_f32_32x32x16_bf16 v[64:79], v[44:47], v[136:139], v[64:79]
	s_waitcnt lgkmcnt(4)
	v_mfma_f32_32x32x16_bf16 v[80:95], v[52:55], v[136:139], v[80:95]
	s_waitcnt lgkmcnt(3)
	v_mfma_f32_32x32x16_bf16 v[64:79], v[56:59], v[132:135], v[64:79]
	s_waitcnt lgkmcnt(2)
	v_mfma_f32_32x32x16_bf16 v[80:95], v[60:63], v[132:135], v[80:95]
	s_waitcnt lgkmcnt(1)
	v_mfma_f32_32x32x16_bf16 v[64:79], v[32:35], v[128:131], v[64:79]
	s_waitcnt lgkmcnt(0)
	v_add_u32_e32 v32, 0x80, v200
	v_cmp_lt_i32_e32 vcc, s4, v32
	v_mfma_f32_32x32x16_bf16 v[80:95], v[36:39], v[128:131], v[80:95]
	v_cvt_f32_i32_e32 v37, v32
	v_cmp_nle_f32_e64 s[36:37], v37, v240
	v_add_f32_e32 v33, 0xc2000000, v37
	v_fma_f32 v0, -v160, v37, v0
	s_or_b64 vcc, vcc, s[36:37]
	v_fma_f32 v34, -v160, v33, v16
	v_cndmask_b32_e32 v16, v0, v235, vcc
	v_cmp_ngt_f32_e32 vcc, s95, v33
	v_cmp_nle_f32_e64 s[36:37], v33, v240
	s_or_b64 vcc, vcc, s[36:37]
	v_add_f32_e32 v32, -1.0, v37
	v_cndmask_b32_e32 v34, v34, v235, vcc
	v_cmp_ngt_f32_e32 vcc, s95, v32
	v_cmp_nle_f32_e64 s[36:37], v32, v240
	v_add_f32_e32 v33, 0xc2000000, v32
	v_fma_f32 v1, -v160, v32, v1
	s_or_b64 vcc, vcc, s[36:37]
	v_fma_f32 v35, -v160, v33, v17
	v_cndmask_b32_e32 v17, v1, v235, vcc
	v_cmp_ngt_f32_e32 vcc, s95, v33
	v_cmp_nle_f32_e64 s[36:37], v33, v240
	s_or_b64 vcc, vcc, s[36:37]
	v_cndmask_b32_e32 v36, v35, v235, vcc
	v_max_f32_e32 v0, v16, v34
	v_max_f32_e32 v1, v17, v36
	v_max3_f32 v0, v0, s94, v1
	v_add_f32_e32 v1, -2.0, v37
	v_cmp_ngt_f32_e32 vcc, s95, v1
	v_cmp_nle_f32_e64 s[36:37], v1, v240
	v_add_f32_e32 v32, 0xc2000000, v1
	v_fma_f32 v2, -v160, v1, v2
	s_or_b64 vcc, vcc, s[36:37]
	v_fma_f32 v33, -v160, v32, v18
	v_cndmask_b32_e32 v18, v2, v235, vcc
	v_cmp_ngt_f32_e32 vcc, s95, v32
	v_cmp_nle_f32_e64 s[36:37], v32, v240
	s_or_b64 vcc, vcc, s[36:37]
	v_add_f32_e32 v2, 0xc0400000, v37
	v_cndmask_b32_e32 v39, v33, v235, vcc
	v_cmp_ngt_f32_e32 vcc, s95, v2
	v_cmp_nle_f32_e64 s[36:37], v2, v240
	v_add_f32_e32 v32, 0xc2000000, v2
	v_fma_f32 v3, -v160, v2, v3
	s_or_b64 vcc, vcc, s[36:37]
	v_fma_f32 v33, -v160, v32, v19
	v_cndmask_b32_e32 v19, v3, v235, vcc
	v_cmp_ngt_f32_e32 vcc, s95, v32
	v_cmp_nle_f32_e64 s[36:37], v32, v240
	s_or_b64 vcc, vcc, s[36:37]
	v_cndmask_b32_e32 v43, v33, v235, vcc
	v_max_f32_e32 v1, v18, v39
	v_max_f32_e32 v2, v19, v43
	v_max3_f32 v0, v0, v1, v2
	v_add_f32_e32 v1, 0xc1000000, v37
	v_cmp_ngt_f32_e32 vcc, s95, v1
	v_cmp_nle_f32_e64 s[36:37], v1, v240
	v_add_f32_e32 v2, 0xc2000000, v1
	v_fma_f32 v3, -v160, v1, v4
	s_or_b64 vcc, vcc, s[36:37]
	v_fma_f32 v4, -v160, v2, v20
	v_cndmask_b32_e32 v20, v3, v235, vcc
	v_cmp_ngt_f32_e32 vcc, s95, v2
	v_cmp_nle_f32_e64 s[36:37], v2, v240
	s_or_b64 vcc, vcc, s[36:37]
	v_add_f32_e32 v2, 0xc1100000, v37
	v_cndmask_b32_e32 v44, v4, v235, vcc
	v_cmp_ngt_f32_e32 vcc, s95, v2
	v_cmp_nle_f32_e64 s[36:37], v2, v240
	v_add_f32_e32 v3, 0xc2000000, v2
	v_fma_f32 v4, -v160, v2, v5
	s_or_b64 vcc, vcc, s[36:37]
	v_fma_f32 v5, -v160, v3, v21
	v_cndmask_b32_e32 v21, v4, v235, vcc
	v_cmp_ngt_f32_e32 vcc, s95, v3
	v_cmp_nle_f32_e64 s[36:37], v3, v240
	s_or_b64 vcc, vcc, s[36:37]
	v_cndmask_b32_e32 v45, v5, v235, vcc
	v_max_f32_e32 v1, v20, v44
	v_max_f32_e32 v2, v21, v45
	v_max3_f32 v0, v0, v1, v2
	v_add_f32_e32 v1, 0xc1200000, v37
	v_cmp_ngt_f32_e32 vcc, s95, v1
	v_cmp_nle_f32_e64 s[36:37], v1, v240
	v_add_f32_e32 v2, 0xc2000000, v1
	v_fma_f32 v3, -v160, v1, v6
	s_or_b64 vcc, vcc, s[36:37]
	v_fma_f32 v4, -v160, v2, v22
	v_cndmask_b32_e32 v22, v3, v235, vcc
	v_cmp_ngt_f32_e32 vcc, s95, v2
	v_cmp_nle_f32_e64 s[36:37], v2, v240
	s_or_b64 vcc, vcc, s[36:37]
	v_add_f32_e32 v2, 0xc1300000, v37
	v_cndmask_b32_e32 v46, v4, v235, vcc
	v_cmp_ngt_f32_e32 vcc, s95, v2
	v_cmp_nle_f32_e64 s[36:37], v2, v240
	v_add_f32_e32 v3, 0xc2000000, v2
	v_fma_f32 v4, -v160, v2, v7
	s_or_b64 vcc, vcc, s[36:37]
	v_fma_f32 v5, -v160, v3, v23
	v_cndmask_b32_e32 v23, v4, v235, vcc
	v_cmp_ngt_f32_e32 vcc, s95, v3
	v_cmp_nle_f32_e64 s[36:37], v3, v240
	s_or_b64 vcc, vcc, s[36:37]
	v_cndmask_b32_e32 v47, v5, v235, vcc
	v_max_f32_e32 v1, v22, v46
	v_max_f32_e32 v2, v23, v47
	v_max3_f32 v0, v0, v1, v2
	v_add_f32_e32 v1, 0xc1800000, v37
	v_cmp_ngt_f32_e32 vcc, s95, v1
	v_cmp_nle_f32_e64 s[36:37], v1, v240
	v_add_f32_e32 v2, 0xc2000000, v1
	v_fma_f32 v3, -v160, v1, v8
	s_or_b64 vcc, vcc, s[36:37]
	v_fma_f32 v4, -v160, v2, v24
	v_cndmask_b32_e32 v24, v3, v235, vcc
	v_cmp_ngt_f32_e32 vcc, s95, v2
	v_cmp_nle_f32_e64 s[36:37], v2, v240
	s_or_b64 vcc, vcc, s[36:37]
	v_add_f32_e32 v2, 0xc1880000, v37
	v_cndmask_b32_e32 v32, v4, v235, vcc
	v_cmp_ngt_f32_e32 vcc, s95, v2
	v_cmp_nle_f32_e64 s[36:37], v2, v240
	v_add_f32_e32 v3, 0xc2000000, v2
	v_fma_f32 v4, -v160, v2, v9
	s_or_b64 vcc, vcc, s[36:37]
	v_fma_f32 v5, -v160, v3, v25
	v_cndmask_b32_e32 v25, v4, v235, vcc
	v_cmp_ngt_f32_e32 vcc, s95, v3
	v_cmp_nle_f32_e64 s[36:37], v3, v240
	s_or_b64 vcc, vcc, s[36:37]
	v_cndmask_b32_e32 v33, v5, v235, vcc
	v_max_f32_e32 v1, v24, v32
	v_max_f32_e32 v2, v25, v33
	v_max3_f32 v0, v0, v1, v2
	v_add_f32_e32 v1, 0xc1900000, v37
	v_cmp_ngt_f32_e32 vcc, s95, v1
	v_cmp_nle_f32_e64 s[36:37], v1, v240
	v_add_f32_e32 v2, 0xc2000000, v1
	v_fma_f32 v3, -v160, v1, v10
	s_or_b64 vcc, vcc, s[36:37]
	v_cndmask_b32_e32 v53, v3, v235, vcc
	v_cmp_ngt_f32_e32 vcc, s95, v2
	v_cmp_nle_f32_e64 s[36:37], v2, v240
	v_fma_f32 v4, -v160, v2, v26
	s_or_b64 vcc, vcc, s[36:37]
	v_add_f32_e32 v2, 0xc1980000, v37
	v_cndmask_b32_e32 v35, v4, v235, vcc
	v_cmp_ngt_f32_e32 vcc, s95, v2
	v_cmp_nle_f32_e64 s[36:37], v2, v240
	v_add_f32_e32 v3, 0xc2000000, v2
	v_fma_f32 v4, -v160, v2, v11
	s_or_b64 vcc, vcc, s[36:37]
	v_fma_f32 v5, -v160, v3, v27
	v_cndmask_b32_e32 v27, v4, v235, vcc
	v_cmp_ngt_f32_e32 vcc, s95, v3
	v_cmp_nle_f32_e64 s[36:37], v3, v240
	s_or_b64 vcc, vcc, s[36:37]
	v_cndmask_b32_e32 v38, v5, v235, vcc
	v_max_f32_e32 v1, v53, v35
	v_max_f32_e32 v2, v27, v38
	v_max3_f32 v0, v0, v1, v2
	v_add_f32_e32 v1, 0xc1c00000, v37
	v_cmp_ngt_f32_e32 vcc, s95, v1
	v_cmp_nle_f32_e64 s[36:37], v1, v240
	v_add_f32_e32 v2, 0xc2000000, v1
	v_fma_f32 v3, -v160, v1, v12
	s_or_b64 vcc, vcc, s[36:37]
	v_fma_f32 v4, -v160, v2, v28
	v_cndmask_b32_e32 v28, v3, v235, vcc
	v_cmp_ngt_f32_e32 vcc, s95, v2
	v_cmp_nle_f32_e64 s[36:37], v2, v240
	s_or_b64 vcc, vcc, s[36:37]
	v_add_f32_e32 v2, 0xc1c80000, v37
	v_cndmask_b32_e32 v40, v4, v235, vcc
	v_cmp_ngt_f32_e32 vcc, s95, v2
	v_cmp_nle_f32_e64 s[36:37], v2, v240
	v_add_f32_e32 v3, 0xc2000000, v2
	v_fma_f32 v4, -v160, v2, v13
	s_or_b64 vcc, vcc, s[36:37]
	v_fma_f32 v5, -v160, v3, v29
	v_cndmask_b32_e32 v29, v4, v235, vcc
	v_cmp_ngt_f32_e32 vcc, s95, v3
	v_cmp_nle_f32_e64 s[36:37], v3, v240
	s_or_b64 vcc, vcc, s[36:37]
	v_cndmask_b32_e32 v42, v5, v235, vcc
	v_max_f32_e32 v1, v28, v40
	v_max_f32_e32 v2, v29, v42
	v_max3_f32 v0, v0, v1, v2
	v_add_f32_e32 v1, 0xc1d00000, v37
	v_cmp_ngt_f32_e32 vcc, s95, v1
	v_cmp_nle_f32_e64 s[36:37], v1, v240
	v_add_f32_e32 v2, 0xc2000000, v1
	v_fma_f32 v3, -v160, v1, v14
	s_or_b64 vcc, vcc, s[36:37]
	v_cndmask_b32_e32 v26, v3, v235, vcc
	v_cmp_ngt_f32_e32 vcc, s95, v2
	v_cmp_nle_f32_e64 s[36:37], v2, v240
	v_fma_f32 v4, -v160, v2, v30
	s_or_b64 vcc, vcc, s[36:37]
	v_add_f32_e32 v2, 0xc1d80000, v37
	v_cndmask_b32_e32 v41, v4, v235, vcc
	v_cmp_ngt_f32_e32 vcc, s95, v2
	v_cmp_nle_f32_e64 s[36:37], v2, v240
	v_add_f32_e32 v3, 0xc2000000, v2
	v_fma_f32 v4, -v160, v2, v15
	s_or_b64 vcc, vcc, s[36:37]
	v_cndmask_b32_e32 v52, v4, v235, vcc
	v_cmp_ngt_f32_e32 vcc, s95, v3
	v_cmp_nle_f32_e64 s[36:37], v3, v240
	v_fma_f32 v5, -v160, v3, v31
	s_or_b64 vcc, vcc, s[36:37]
	v_cndmask_b32_e32 v37, v5, v235, vcc
	v_max_f32_e32 v1, v26, v41
	v_max_f32_e32 v2, v52, v37
	v_max3_f32 v0, v0, v1, v2
	v_mov_b32_e32 v1, v0
	v_mov_b32_e32 v2, v0
	s_nop 1
	v_permlane32_swap_b32_e32 v1, v2
	v_cndmask_b32_e64 v1, v1, v2, s[34:35]
	v_max3_f32 v241, v196, v0, v1
	v_sub_f32_e32 v0, v196, v241
	v_exp_f32_e32 v199, v0
	s_nop 0
	v_cmp_neq_f32_e32 vcc, 1.0, v199
	s_cbranch_vccz .LBB0_488
	s_and_saveexec_b64 s[4:5], s[34:35]
	ds_write_b32 v190, v199
	s_or_b64 exec, exec, s[4:5]
	v_add_u32_e32 v8, s38, v144
	ds_read_b128 v[0:3], v8 offset:96
	ds_read_b128 v[4:7], v8 offset:64
	ds_read_b128 v[54:57], v8 offset:32
	ds_read_b128 v[58:61], v8
	s_waitcnt lgkmcnt(3)
	v_pk_mul_f32 v[14:15], v[2:3], 0 op_sel_hi:[1,0]
	s_waitcnt lgkmcnt(2)
	v_pk_mul_f32 v[10:11], v[6:7], 0 op_sel_hi:[1,0]
	s_waitcnt lgkmcnt(1)
	v_pk_mul_f32 v[6:7], v[56:57], 0 op_sel_hi:[1,0]
	s_waitcnt lgkmcnt(0)
	v_pk_mul_f32 v[2:3], v[60:61], 0 op_sel_hi:[1,0]
	v_pk_mul_f32 v[12:13], v[0:1], 0 op_sel_hi:[1,0]
	v_pk_mul_f32 v[8:9], v[4:5], 0 op_sel_hi:[1,0]
	v_pk_mul_f32 v[4:5], v[54:55], 0 op_sel_hi:[1,0]
	v_pk_mul_f32 v[0:1], v[58:59], 0 op_sel_hi:[1,0]
	s_branch .LBB0_489
